# S5 diagonal recurrence: x read 4 steps ahead with counted lgkmcnt (was one LDS round trip per step), both S5 passes
# speedup vs baseline: 1.0033x; 1.0033x over previous
.LBB0_1049:
	s_or_b64 exec, exec, s[46:47]
	v_mfma_f32_16x16x32_bf16 v[58:61], v[34:37], v[2:5], 0
	v_add_u32_e32 v74, 0x400, v54
	s_xor_b64 s[44:45], s[44:45], -1
	s_mov_b32 s7, 16
	v_mfma_f32_16x16x32_bf16 v[62:65], v[34:37], v[6:9], 0
	s_nop 7
	ds_write2_b32 v54, v58, v62 offset1:16
	ds_write2_b32 v54, v59, v63 offset0:132 offset1:148
	v_mfma_f32_16x16x32_bf16 v[70:73], v[34:37], v[14:17], 0
	ds_write2_b32 v74, v60, v64 offset0:8 offset1:24
	ds_write2_b32 v74, v61, v65 offset0:140 offset1:156
	s_nop 5
	ds_write2_b32 v55, v70, v71 offset1:132
	v_add_u32_e32 v62, 0x400, v55
	v_mfma_f32_16x16x32_bf16 v[66:69], v[34:37], v[10:13], 0
	s_andn2_b64 vcc, exec, s[44:45]
	s_mov_b64 s[44:45], 0
	v_mfma_f32_16x16x32_bf16 v[58:61], v[34:37], v[18:21], 0
	ds_write2_b32 v62, v72, v73 offset0:8 offset1:140
	s_nop 6
	ds_write2_b32 v54, v66, v58 offset0:32 offset1:64
	v_mfma_f32_16x16x32_bf16 v[62:65], v[34:37], v[22:25], 0
	ds_write2_b32 v54, v67, v59 offset0:164 offset1:196
	ds_write2_b32 v74, v68, v60 offset0:40 offset1:72
	ds_write2_b32 v74, v69, v61 offset0:172 offset1:204
	v_mfma_f32_16x16x32_bf16 v[58:61], v[34:37], v[26:29], 0
	s_nop 7
	ds_write2_b32 v54, v62, v58 offset0:80 offset1:96
	ds_write2_b32 v54, v63, v59 offset0:212 offset1:228
	ds_write2_b32 v74, v64, v60 offset0:88 offset1:104
	ds_write2_b32 v74, v65, v61 offset0:220 offset1:236
	v_mfma_f32_16x16x32_bf16 v[34:37], v[34:37], v[30:33], 0
	s_nop 7
	ds_write2_b32 v56, v34, v35 offset1:132
	v_add_u32_e32 v34, 0x400, v56
	ds_write2_b32 v34, v36, v37 offset0:8 offset1:140
	s_waitcnt lgkmcnt(0)
	v_add_u32_e32 v108, 16, v53
	v_add_u32_e32 v109, 32, v53
	v_add_u32_e32 v110, 48, v53
	v_add_u32_e32 v111, 64, v53
	v_add_u32_e32 v112, 80, v53
	v_add_u32_e32 v113, 96, v53
	v_add_u32_e32 v114, 112, v53
	v_add_u32_e32 v115, 128, v53
	v_add_u32_e32 v116, 144, v53
	v_add_u32_e32 v117, 160, v53
	v_add_u32_e32 v118, 176, v53
	v_add_u32_e32 v119, 192, v53
	v_add_u32_e32 v120, 208, v53
	v_add_u32_e32 v121, 224, v53
	v_add_u32_e32 v122, 240, v53
	ds_read2st64_b32 v[100:101], v53 offset0:0 offset1:1
	ds_read2st64_b32 v[102:103], v108 offset0:2 offset1:3
	ds_read2st64_b32 v[104:105], v109 offset0:4 offset1:5
	ds_read2st64_b32 v[106:107], v110 offset0:6 offset1:7
	s_waitcnt lgkmcnt(3)
	v_mul_f32_e32 v123, v47, v51
	v_fma_f32 v123, v46, v50, -v123
	v_mul_f32_e32 v124, v46, v51
	v_fmac_f32_e32 v124, v47, v50
	v_add_f32_e32 v125, v123, v100
	v_add_f32_e32 v126, v124, v101
	ds_read2st64_b32 v[100:101], v111 offset0:8 offset1:9
	s_waitcnt lgkmcnt(3)
	v_mul_f32_e32 v123, v47, v126
	v_fma_f32 v123, v46, v125, -v123
	v_mul_f32_e32 v124, v46, v126
	v_fmac_f32_e32 v124, v47, v125
	v_add_f32_e32 v127, v123, v102
	v_add_f32_e32 v128, v124, v103
	ds_read2st64_b32 v[102:103], v112 offset0:10 offset1:11
	s_waitcnt lgkmcnt(3)
	v_mul_f32_e32 v123, v47, v128
	v_fma_f32 v123, v46, v127, -v123
	v_mul_f32_e32 v124, v46, v128
	v_fmac_f32_e32 v124, v47, v127
	v_add_f32_e32 v125, v123, v104
	v_add_f32_e32 v126, v124, v105
	ds_read2st64_b32 v[104:105], v113 offset0:12 offset1:13
	s_waitcnt lgkmcnt(3)
	v_mul_f32_e32 v123, v47, v126
	v_fma_f32 v123, v46, v125, -v123
	v_mul_f32_e32 v124, v46, v126
	v_fmac_f32_e32 v124, v47, v125
	v_add_f32_e32 v127, v123, v106
	v_add_f32_e32 v128, v124, v107
	ds_read2st64_b32 v[106:107], v114 offset0:14 offset1:15
	s_waitcnt lgkmcnt(3)
	v_mul_f32_e32 v123, v47, v128
	v_fma_f32 v123, v46, v127, -v123
	v_mul_f32_e32 v124, v46, v128
	v_fmac_f32_e32 v124, v47, v127
	v_add_f32_e32 v125, v123, v100
	v_add_f32_e32 v126, v124, v101
	ds_read2st64_b32 v[100:101], v115 offset0:16 offset1:17
	s_waitcnt lgkmcnt(3)
	v_mul_f32_e32 v123, v47, v126
	v_fma_f32 v123, v46, v125, -v123
	v_mul_f32_e32 v124, v46, v126
	v_fmac_f32_e32 v124, v47, v125
	v_add_f32_e32 v127, v123, v102
	v_add_f32_e32 v128, v124, v103
	ds_read2st64_b32 v[102:103], v116 offset0:18 offset1:19
	s_waitcnt lgkmcnt(3)
	v_mul_f32_e32 v123, v47, v128
	v_fma_f32 v123, v46, v127, -v123
	v_mul_f32_e32 v124, v46, v128
	v_fmac_f32_e32 v124, v47, v127
	v_add_f32_e32 v125, v123, v104
	v_add_f32_e32 v126, v124, v105
	ds_read2st64_b32 v[104:105], v117 offset0:20 offset1:21
	s_waitcnt lgkmcnt(3)
	v_mul_f32_e32 v123, v47, v126
	v_fma_f32 v123, v46, v125, -v123
	v_mul_f32_e32 v124, v46, v126
	v_fmac_f32_e32 v124, v47, v125
	v_add_f32_e32 v127, v123, v106
	v_add_f32_e32 v128, v124, v107
	ds_read2st64_b32 v[106:107], v118 offset0:22 offset1:23
	s_waitcnt lgkmcnt(3)
	v_mul_f32_e32 v123, v47, v128
	v_fma_f32 v123, v46, v127, -v123
	v_mul_f32_e32 v124, v46, v128
	v_fmac_f32_e32 v124, v47, v127
	v_add_f32_e32 v125, v123, v100
	v_add_f32_e32 v126, v124, v101
	ds_read2st64_b32 v[100:101], v119 offset0:24 offset1:25
	s_waitcnt lgkmcnt(3)
	v_mul_f32_e32 v123, v47, v126
	v_fma_f32 v123, v46, v125, -v123
	v_mul_f32_e32 v124, v46, v126
	v_fmac_f32_e32 v124, v47, v125
	v_add_f32_e32 v127, v123, v102
	v_add_f32_e32 v128, v124, v103
	ds_read2st64_b32 v[102:103], v120 offset0:26 offset1:27
	s_waitcnt lgkmcnt(3)
	v_mul_f32_e32 v123, v47, v128
	v_fma_f32 v123, v46, v127, -v123
	v_mul_f32_e32 v124, v46, v128
	v_fmac_f32_e32 v124, v47, v127
	v_add_f32_e32 v125, v123, v104
	v_add_f32_e32 v126, v124, v105
	ds_read2st64_b32 v[104:105], v121 offset0:28 offset1:29
	s_waitcnt lgkmcnt(3)
	v_mul_f32_e32 v123, v47, v126
	v_fma_f32 v123, v46, v125, -v123
	v_mul_f32_e32 v124, v46, v126
	v_fmac_f32_e32 v124, v47, v125
	v_add_f32_e32 v127, v123, v106
	v_add_f32_e32 v128, v124, v107
	ds_read2st64_b32 v[106:107], v122 offset0:30 offset1:31
	s_waitcnt lgkmcnt(3)
	v_mul_f32_e32 v123, v47, v128
	v_fma_f32 v123, v46, v127, -v123
	v_mul_f32_e32 v124, v46, v128
	v_fmac_f32_e32 v124, v47, v127
	v_add_f32_e32 v125, v123, v100
	v_add_f32_e32 v126, v124, v101
	s_waitcnt lgkmcnt(2)
	v_mul_f32_e32 v123, v47, v126
	v_fma_f32 v123, v46, v125, -v123
	v_mul_f32_e32 v124, v46, v126
	v_fmac_f32_e32 v124, v47, v125
	v_add_f32_e32 v127, v123, v102
	v_add_f32_e32 v128, v124, v103
	s_waitcnt lgkmcnt(1)
	v_mul_f32_e32 v123, v47, v128
	v_fma_f32 v123, v46, v127, -v123
	v_mul_f32_e32 v124, v46, v128
	v_fmac_f32_e32 v124, v47, v127
	v_add_f32_e32 v125, v123, v104
	v_add_f32_e32 v126, v124, v105
	s_waitcnt lgkmcnt(0)
	v_mul_f32_e32 v123, v47, v126
	v_fma_f32 v123, v46, v125, -v123
	v_mul_f32_e32 v124, v46, v126
	v_fmac_f32_e32 v124, v47, v125
	v_add_f32_e32 v50, v123, v106
	v_add_f32_e32 v51, v124, v107
	s_cbranch_vccz .LBB0_1047

.LBB0_1198:
	s_or_b64 exec, exec, s[6:7]
	v_mfma_f32_16x16x32_bf16 v[114:117], v[60:63], v[8:11], 0
	v_lshl_add_u64 v[56:57], v[56:57], 0, v[0:1]
	v_add_u32_e32 v83, 0x400, v101
	v_mov_b32_e32 v56, v140
	v_mov_b32_e32 v57, v141
	v_mov_b32_e32 v58, v142
	v_mov_b32_e32 v59, v143
	v_mfma_f32_16x16x32_bf16 v[118:121], v[60:63], v[12:15], 0
	s_nop 7
	ds_write2_b32 v101, v114, v118 offset1:16
	ds_write2_b32 v101, v115, v119 offset0:132 offset1:148
	ds_write2_b32 v83, v116, v120 offset0:8 offset1:24
	ds_write2_b32 v83, v117, v121 offset0:140 offset1:156
	v_mfma_f32_16x16x32_bf16 v[114:117], v[60:63], v[16:19], 0
	s_nop 7
	ds_write_b32 v101, v114 offset:128
	ds_write_b32 v101, v115 offset:656
	ds_write_b32 v101, v116 offset:1184
	ds_write_b32 v101, v117 offset:1712
	v_mfma_f32_16x16x32_bf16 v[114:117], v[60:63], v[20:23], 0
	v_add_u32_e32 v93, 0x400, v103
	s_xor_b64 s[6:7], s[38:39], -1
	s_mov_b64 s[38:39], 0
	v_mfma_f32_16x16x32_bf16 v[118:121], v[60:63], v[28:31], 0
	s_nop 3
	ds_write2_b32 v103, v114, v115 offset1:132
	ds_write2_b32 v93, v116, v117 offset0:8 offset1:140
	v_mfma_f32_16x16x32_bf16 v[114:117], v[60:63], v[24:27], 0
	s_nop 7
	ds_write2_b32 v101, v114, v118 offset0:64 offset1:80
	ds_write2_b32 v101, v115, v119 offset0:196 offset1:212
	ds_write2_b32 v83, v116, v120 offset0:72 offset1:88
	ds_write2_b32 v83, v117, v121 offset0:204 offset1:220
	v_mfma_f32_16x16x32_bf16 v[114:117], v[60:63], v[32:35], 0
	s_nop 7
	ds_write_b32 v101, v114 offset:384
	ds_write_b32 v101, v115 offset:912
	ds_write_b32 v101, v116 offset:1440
	ds_write_b32 v101, v117 offset:1968
	v_mfma_f32_16x16x32_bf16 v[60:63], v[60:63], v[36:39], 0
	s_nop 7
	ds_write2_b32 v104, v60, v61 offset1:132
	v_add_u32_e32 v60, 0x400, v104
	ds_write2_b32 v60, v62, v63 offset0:8 offset1:140
	s_waitcnt lgkmcnt(0)
	v_add_u32_e32 v164, 16, v105
	v_add_u32_e32 v165, 32, v105
	v_add_u32_e32 v166, 48, v105
	v_add_u32_e32 v167, 64, v105
	v_add_u32_e32 v168, 80, v105
	v_add_u32_e32 v169, 96, v105
	v_add_u32_e32 v170, 112, v105
	v_add_u32_e32 v171, 128, v105
	v_add_u32_e32 v172, 144, v105
	v_add_u32_e32 v173, 160, v105
	v_add_u32_e32 v174, 176, v105
	v_add_u32_e32 v175, 192, v105
	v_add_u32_e32 v176, 208, v105
	v_add_u32_e32 v177, 224, v105
	v_add_u32_e32 v218, 240, v105
	ds_read2st64_b32 v[156:157], v105 offset0:0 offset1:1
	ds_read2st64_b32 v[158:159], v164 offset0:2 offset1:3
	ds_read2st64_b32 v[160:161], v165 offset0:4 offset1:5
	ds_read2st64_b32 v[162:163], v166 offset0:6 offset1:7
	s_waitcnt lgkmcnt(3)
	v_mul_f32_e32 v212, v3, v97
	v_fma_f32 v212, v2, v96, -v212
	v_mul_f32_e32 v213, v2, v97
	v_fmac_f32_e32 v213, v3, v96
	v_add_f32_e32 v214, v212, v156
	v_add_f32_e32 v215, v213, v157
	ds_read2st64_b32 v[156:157], v167 offset0:8 offset1:9
	ds_write2st64_b32 v105, v214, v215 offset0:0 offset1:1
	s_waitcnt lgkmcnt(4)
	v_mul_f32_e32 v212, v3, v215
	v_fma_f32 v212, v2, v214, -v212
	v_mul_f32_e32 v213, v2, v215
	v_fmac_f32_e32 v213, v3, v214
	v_add_f32_e32 v216, v212, v158
	v_add_f32_e32 v217, v213, v159
	ds_read2st64_b32 v[158:159], v168 offset0:10 offset1:11
	ds_write2st64_b32 v164, v216, v217 offset0:2 offset1:3
	s_waitcnt lgkmcnt(5)
	v_mul_f32_e32 v212, v3, v217
	v_fma_f32 v212, v2, v216, -v212
	v_mul_f32_e32 v213, v2, v217
	v_fmac_f32_e32 v213, v3, v216
	v_add_f32_e32 v214, v212, v160
	v_add_f32_e32 v215, v213, v161
	ds_read2st64_b32 v[160:161], v169 offset0:12 offset1:13
	ds_write2st64_b32 v165, v214, v215 offset0:4 offset1:5
	s_waitcnt lgkmcnt(6)
	v_mul_f32_e32 v212, v3, v215
	v_fma_f32 v212, v2, v214, -v212
	v_mul_f32_e32 v213, v2, v215
	v_fmac_f32_e32 v213, v3, v214
	v_add_f32_e32 v216, v212, v162
	v_add_f32_e32 v217, v213, v163
	ds_read2st64_b32 v[162:163], v170 offset0:14 offset1:15
	ds_write2st64_b32 v166, v216, v217 offset0:6 offset1:7
	s_waitcnt lgkmcnt(7)
	v_mul_f32_e32 v212, v3, v217
	v_fma_f32 v212, v2, v216, -v212
	v_mul_f32_e32 v213, v2, v217
	v_fmac_f32_e32 v213, v3, v216
	v_add_f32_e32 v214, v212, v156
	v_add_f32_e32 v215, v213, v157
	ds_read2st64_b32 v[156:157], v171 offset0:16 offset1:17
	ds_write2st64_b32 v167, v214, v215 offset0:8 offset1:9
	s_waitcnt lgkmcnt(7)
	v_mul_f32_e32 v212, v3, v215
	v_fma_f32 v212, v2, v214, -v212
	v_mul_f32_e32 v213, v2, v215
	v_fmac_f32_e32 v213, v3, v214
	v_add_f32_e32 v216, v212, v158
	v_add_f32_e32 v217, v213, v159
	ds_read2st64_b32 v[158:159], v172 offset0:18 offset1:19
	ds_write2st64_b32 v168, v216, v217 offset0:10 offset1:11
	s_waitcnt lgkmcnt(7)
	v_mul_f32_e32 v212, v3, v217
	v_fma_f32 v212, v2, v216, -v212
	v_mul_f32_e32 v213, v2, v217
	v_fmac_f32_e32 v213, v3, v216
	v_add_f32_e32 v214, v212, v160
	v_add_f32_e32 v215, v213, v161
	ds_read2st64_b32 v[160:161], v173 offset0:20 offset1:21
	ds_write2st64_b32 v169, v214, v215 offset0:12 offset1:13
	s_waitcnt lgkmcnt(7)
	v_mul_f32_e32 v212, v3, v215
	v_fma_f32 v212, v2, v214, -v212
	v_mul_f32_e32 v213, v2, v215
	v_fmac_f32_e32 v213, v3, v214
	v_add_f32_e32 v216, v212, v162
	v_add_f32_e32 v217, v213, v163
	ds_read2st64_b32 v[162:163], v174 offset0:22 offset1:23
	ds_write2st64_b32 v170, v216, v217 offset0:14 offset1:15
	s_waitcnt lgkmcnt(7)
	v_mul_f32_e32 v212, v3, v217
	v_fma_f32 v212, v2, v216, -v212
	v_mul_f32_e32 v213, v2, v217
	v_fmac_f32_e32 v213, v3, v216
	v_add_f32_e32 v214, v212, v156
	v_add_f32_e32 v215, v213, v157
	ds_read2st64_b32 v[156:157], v175 offset0:24 offset1:25
	ds_write2st64_b32 v171, v214, v215 offset0:16 offset1:17
	s_waitcnt lgkmcnt(7)
	v_mul_f32_e32 v212, v3, v215
	v_fma_f32 v212, v2, v214, -v212
	v_mul_f32_e32 v213, v2, v215
	v_fmac_f32_e32 v213, v3, v214
	v_add_f32_e32 v216, v212, v158
	v_add_f32_e32 v217, v213, v159
	ds_read2st64_b32 v[158:159], v176 offset0:26 offset1:27
	ds_write2st64_b32 v172, v216, v217 offset0:18 offset1:19
	s_waitcnt lgkmcnt(7)
	v_mul_f32_e32 v212, v3, v217
	v_fma_f32 v212, v2, v216, -v212
	v_mul_f32_e32 v213, v2, v217
	v_fmac_f32_e32 v213, v3, v216
	v_add_f32_e32 v214, v212, v160
	v_add_f32_e32 v215, v213, v161
	ds_read2st64_b32 v[160:161], v177 offset0:28 offset1:29
	ds_write2st64_b32 v173, v214, v215 offset0:20 offset1:21
	s_waitcnt lgkmcnt(7)
	v_mul_f32_e32 v212, v3, v215
	v_fma_f32 v212, v2, v214, -v212
	v_mul_f32_e32 v213, v2, v215
	v_fmac_f32_e32 v213, v3, v214
	v_add_f32_e32 v216, v212, v162
	v_add_f32_e32 v217, v213, v163
	ds_read2st64_b32 v[162:163], v218 offset0:30 offset1:31
	ds_write2st64_b32 v174, v216, v217 offset0:22 offset1:23
	s_waitcnt lgkmcnt(7)
	v_mul_f32_e32 v212, v3, v217
	v_fma_f32 v212, v2, v216, -v212
	v_mul_f32_e32 v213, v2, v217
	v_fmac_f32_e32 v213, v3, v216
	v_add_f32_e32 v214, v212, v156
	v_add_f32_e32 v215, v213, v157
	ds_write2st64_b32 v175, v214, v215 offset0:24 offset1:25
	s_waitcnt lgkmcnt(6)
	v_mul_f32_e32 v212, v3, v215
	v_fma_f32 v212, v2, v214, -v212
	v_mul_f32_e32 v213, v2, v215
	v_fmac_f32_e32 v213, v3, v214
	v_add_f32_e32 v216, v212, v158
	v_add_f32_e32 v217, v213, v159
	ds_write2st64_b32 v176, v216, v217 offset0:26 offset1:27
	s_waitcnt lgkmcnt(5)
	v_mul_f32_e32 v212, v3, v217
	v_fma_f32 v212, v2, v216, -v212
	v_mul_f32_e32 v213, v2, v217
	v_fmac_f32_e32 v213, v3, v216
	v_add_f32_e32 v214, v212, v160
	v_add_f32_e32 v215, v213, v161
	ds_write2st64_b32 v177, v214, v215 offset0:28 offset1:29
	s_waitcnt lgkmcnt(4)
	v_mul_f32_e32 v212, v3, v215
	v_fma_f32 v212, v2, v214, -v212
	v_mul_f32_e32 v213, v2, v215
	v_fmac_f32_e32 v213, v3, v214
	v_add_f32_e32 v96, v212, v162
	v_add_f32_e32 v97, v213, v163
	ds_write2st64_b32 v218, v96, v97 offset0:30 offset1:31
	s_waitcnt lgkmcnt(0)
	ds_read_b128 v[60:63], v100
	ds_read_b128 v[114:117], v100 offset:16
	s_waitcnt lgkmcnt(0)
	v_bfe_u32 v83, v60, 16, 1
	v_add3_u32 v60, v60, v83, s23
	v_bfe_u32 v83, v61, 16, 1
	v_lshrrev_b32_e32 v60, 16, v60
	v_add3_u32 v61, v61, v83, s23
	v_and_or_b32 v60, v61, s15, v60
	v_and_b32_sdwa v61, v63, v225 dst_sel:DWORD dst_unused:UNUSED_PAD src0_sel:WORD_1 src1_sel:DWORD
	v_and_b32_sdwa v83, v62, v225 dst_sel:DWORD dst_unused:UNUSED_PAD src0_sel:WORD_1 src1_sel:DWORD
	v_add3_u32 v62, v62, v83, s23
	v_add3_u32 v61, v63, v61, s23
	v_perm_b32 v61, v61, v62, s22
	v_and_b32_sdwa v62, v115, v225 dst_sel:DWORD dst_unused:UNUSED_PAD src0_sel:WORD_1 src1_sel:DWORD
	v_and_b32_sdwa v63, v114, v225 dst_sel:DWORD dst_unused:UNUSED_PAD src0_sel:WORD_1 src1_sel:DWORD
	v_add3_u32 v63, v114, v63, s23
	v_add3_u32 v62, v115, v62, s23
	v_perm_b32 v62, v62, v63, s22
	v_and_b32_sdwa v63, v117, v225 dst_sel:DWORD dst_unused:UNUSED_PAD src0_sel:WORD_1 src1_sel:DWORD
	v_and_b32_sdwa v83, v116, v225 dst_sel:DWORD dst_unused:UNUSED_PAD src0_sel:WORD_1 src1_sel:DWORD
	v_add3_u32 v83, v116, v83, s23
	v_add3_u32 v63, v117, v63, s23
	ds_read_b128 v[114:117], v100 offset:128
	ds_read_b128 v[118:121], v100 offset:144
	v_perm_b32 v63, v63, v83, s22
	s_waitcnt lgkmcnt(0)
	v_bfe_u32 v83, v114, 16, 1
	v_add3_u32 v83, v114, v83, s23
	v_bfe_u32 v93, v115, 16, 1
	v_lshrrev_b32_e32 v83, 16, v83
	v_add3_u32 v93, v115, v93, s23
	v_and_or_b32 v114, v93, s15, v83
	v_and_b32_sdwa v83, v117, v225 dst_sel:DWORD dst_unused:UNUSED_PAD src0_sel:WORD_1 src1_sel:DWORD
	v_and_b32_sdwa v93, v116, v225 dst_sel:DWORD dst_unused:UNUSED_PAD src0_sel:WORD_1 src1_sel:DWORD
	v_add3_u32 v93, v116, v93, s23
	v_add3_u32 v83, v117, v83, s23
	v_perm_b32 v115, v83, v93, s22
	v_and_b32_sdwa v83, v119, v225 dst_sel:DWORD dst_unused:UNUSED_PAD src0_sel:WORD_1 src1_sel:DWORD
	v_and_b32_sdwa v93, v118, v225 dst_sel:DWORD dst_unused:UNUSED_PAD src0_sel:WORD_1 src1_sel:DWORD
	v_mfma_f32_16x16x32_bf16 v[60:63], v[40:43], v[60:63], 0
	v_add3_u32 v93, v118, v93, s23
	v_add3_u32 v83, v119, v83, s23
	v_perm_b32 v116, v83, v93, s22
	v_and_b32_sdwa v83, v121, v225 dst_sel:DWORD dst_unused:UNUSED_PAD src0_sel:WORD_1 src1_sel:DWORD
	v_and_b32_sdwa v93, v120, v225 dst_sel:DWORD dst_unused:UNUSED_PAD src0_sel:WORD_1 src1_sel:DWORD
	v_add3_u32 v93, v120, v93, s23
	v_add3_u32 v83, v121, v83, s23
	v_perm_b32 v117, v83, v93, s22
	s_nop 1
	v_mfma_f32_16x16x32_bf16 v[60:63], v[44:47], v[114:117], v[60:63]
	ds_read_b128 v[114:117], v100 offset:256
	ds_read_b128 v[118:121], v100 offset:272
	s_waitcnt lgkmcnt(0)
	v_bfe_u32 v83, v114, 16, 1
	v_add3_u32 v83, v114, v83, s23
	v_bfe_u32 v93, v115, 16, 1
	v_lshrrev_b32_e32 v83, 16, v83
	v_add3_u32 v93, v115, v93, s23
	v_and_or_b32 v114, v93, s15, v83
	v_and_b32_sdwa v83, v117, v225 dst_sel:DWORD dst_unused:UNUSED_PAD src0_sel:WORD_1 src1_sel:DWORD
	v_and_b32_sdwa v93, v116, v225 dst_sel:DWORD dst_unused:UNUSED_PAD src0_sel:WORD_1 src1_sel:DWORD
	v_add3_u32 v93, v116, v93, s23
	v_add3_u32 v83, v117, v83, s23
	v_perm_b32 v115, v83, v93, s22
	v_and_b32_sdwa v83, v119, v225 dst_sel:DWORD dst_unused:UNUSED_PAD src0_sel:WORD_1 src1_sel:DWORD
	v_and_b32_sdwa v93, v118, v225 dst_sel:DWORD dst_unused:UNUSED_PAD src0_sel:WORD_1 src1_sel:DWORD
	v_add3_u32 v93, v118, v93, s23
	v_add3_u32 v83, v119, v83, s23
	v_perm_b32 v116, v83, v93, s22
	v_and_b32_sdwa v83, v121, v225 dst_sel:DWORD dst_unused:UNUSED_PAD src0_sel:WORD_1 src1_sel:DWORD
	v_and_b32_sdwa v93, v120, v225 dst_sel:DWORD dst_unused:UNUSED_PAD src0_sel:WORD_1 src1_sel:DWORD
	v_add3_u32 v93, v120, v93, s23
	v_add3_u32 v83, v121, v83, s23
	v_perm_b32 v117, v83, v93, s22
	s_nop 1
	v_mfma_f32_16x16x32_bf16 v[60:63], v[48:51], v[114:117], v[60:63]
	ds_read_b128 v[114:117], v100 offset:384
	ds_read_b128 v[118:121], v100 offset:400
	s_waitcnt lgkmcnt(0)
	s_waitcnt lgkmcnt(0)
	v_bfe_u32 v83, v114, 16, 1
	v_add3_u32 v83, v114, v83, s23
	v_bfe_u32 v93, v115, 16, 1
	v_lshrrev_b32_e32 v83, 16, v83
	v_add3_u32 v93, v115, v93, s23
	v_and_or_b32 v114, v93, s15, v83
	v_and_b32_sdwa v83, v117, v225 dst_sel:DWORD dst_unused:UNUSED_PAD src0_sel:WORD_1 src1_sel:DWORD
	v_and_b32_sdwa v93, v116, v225 dst_sel:DWORD dst_unused:UNUSED_PAD src0_sel:WORD_1 src1_sel:DWORD
	v_add3_u32 v93, v116, v93, s23
	v_add3_u32 v83, v117, v83, s23
	v_perm_b32 v115, v83, v93, s22
	v_and_b32_sdwa v83, v119, v225 dst_sel:DWORD dst_unused:UNUSED_PAD src0_sel:WORD_1 src1_sel:DWORD
	v_and_b32_sdwa v93, v118, v225 dst_sel:DWORD dst_unused:UNUSED_PAD src0_sel:WORD_1 src1_sel:DWORD
	v_add3_u32 v93, v118, v93, s23
	v_add3_u32 v83, v119, v83, s23
	v_perm_b32 v116, v83, v93, s22
	v_and_b32_sdwa v83, v121, v225 dst_sel:DWORD dst_unused:UNUSED_PAD src0_sel:WORD_1 src1_sel:DWORD
	v_and_b32_sdwa v93, v120, v225 dst_sel:DWORD dst_unused:UNUSED_PAD src0_sel:WORD_1 src1_sel:DWORD
	v_add3_u32 v93, v120, v93, s23
	v_add3_u32 v83, v121, v83, s23
	v_perm_b32 v117, v83, v93, s22
	s_nop 1
	v_mfma_f32_16x16x32_bf16 v[60:63], v[52:55], v[114:117], v[60:63]
	s_waitcnt vmcnt(0)
	s_nop 6
	v_pk_fma_f32 v[56:57], v[4:5], v[56:57], v[60:61]
	v_pk_fma_f32 v[58:59], v[6:7], v[58:59], v[62:63]
	v_mul_f32_e32 v62, 0x3d372713, v56
	v_mul_f32_e32 v83, 0x3d372713, v57
	v_mul_f32_e32 v62, v56, v62
	v_mul_f32_e32 v83, v57, v83
	v_mov_b32_e32 v60, v56
	v_fma_f32 v56, v56, v62, v56
	v_mov_b32_e32 v62, v57
	v_fmac_f32_e32 v57, v57, v83
	v_mul_f32_e32 v57, 0x3f4c422a, v57
	v_add_f32_e32 v57, v57, v57
	v_mul_f32_e32 v57, 0x3fb8aa3b, v57
	v_exp_f32_e32 v114, v57
	v_mul_f32_e32 v57, 0x3d372713, v58
	v_mul_f32_e32 v57, v58, v57
	v_fma_f32 v57, v58, v57, v58
	v_mul_f32_e32 v56, 0x3f4c422a, v56
	v_mul_f32_e32 v57, 0x3f4c422a, v57
	v_add_f32_e32 v56, v56, v56
	v_add_f32_e32 v57, v57, v57
	v_mul_f32_e32 v56, 0x3fb8aa3b, v56
	v_mul_f32_e32 v57, 0x3fb8aa3b, v57
	v_exp_f32_e32 v56, v56
	v_exp_f32_e32 v57, v57
	v_mov_b32_e32 v61, v58
	v_mov_b32_e32 v63, v59
	v_pk_mul_f32 v[60:61], v[60:61], 0.5 op_sel_hi:[1,0]
	v_pk_add_f32 v[56:57], v[56:57], 1.0 op_sel_hi:[1,0]
	s_nop 0
	s_nop 0
	v_rcp_f32_e32 v57, v57
	s_nop 0
	s_nop 0
	v_rcp_f32_e32 v56, v56
	s_nop 0
	v_mul_f32_e32 v58, 0x3d372713, v59
	v_mul_f32_e32 v58, v59, v58
	v_fmac_f32_e32 v59, v59, v58
	v_mul_f32_e32 v58, 0x3f4c422a, v59
	v_add_f32_e32 v58, v58, v58
	v_mul_f32_e32 v58, 0x3fb8aa3b, v58
	v_exp_f32_e32 v115, v58
	v_pk_fma_f32 v[56:57], v[56:57], 2.0, 1.0 op_sel_hi:[1,0,0] neg_lo:[1,0,0] neg_hi:[1,0,0]
	v_pk_add_f32 v[58:59], v[114:115], 1.0 op_sel_hi:[1,0]
	v_pk_add_f32 v[56:57], v[56:57], 1.0 op_sel_hi:[1,0]
	s_nop 0
	v_pk_mul_f32 v[56:57], v[60:61], v[56:57]
	s_nop 0
	v_rcp_f32_e32 v59, v59
	s_nop 0
	s_nop 0
	v_rcp_f32_e32 v58, v58
	s_nop 0
	v_pk_fma_f32 v[58:59], v[58:59], 2.0, 1.0 op_sel_hi:[1,0,0] neg_lo:[1,0,0] neg_hi:[1,0,0]
	v_pk_mul_f32 v[60:61], v[62:63], 0.5 op_sel_hi:[1,0]
	v_pk_add_f32 v[58:59], v[58:59], 1.0 op_sel_hi:[1,0]
	s_andn2_b64 vcc, exec, s[6:7]
	v_pk_mul_f32 v[58:59], v[60:61], v[58:59]
	v_and_b32_sdwa v61, v56, v225 dst_sel:DWORD dst_unused:UNUSED_PAD src0_sel:WORD_1 src1_sel:DWORD
	v_and_b32_sdwa v60, v57, v225 dst_sel:DWORD dst_unused:UNUSED_PAD src0_sel:WORD_1 src1_sel:DWORD
	v_add3_u32 v56, v56, v61, s23
	v_and_b32_sdwa v61, v58, v225 dst_sel:DWORD dst_unused:UNUSED_PAD src0_sel:WORD_1 src1_sel:DWORD
	v_add3_u32 v57, v57, v60, s23
	v_and_b32_sdwa v60, v59, v225 dst_sel:DWORD dst_unused:UNUSED_PAD src0_sel:WORD_1 src1_sel:DWORD
	v_add3_u32 v58, v58, v61, s23
	v_add3_u32 v59, v59, v60, s23
	v_and_b32_e32 v58, 0xffff0000, v58
	v_and_b32_e32 v59, 0xffff0000, v59
	v_or_b32_sdwa v56, v58, v56 dst_sel:DWORD dst_unused:UNUSED_PAD src0_sel:DWORD src1_sel:WORD_1
	v_or_b32_e32 v58, s18, v64
	v_or_b32_sdwa v57, v59, v57 dst_sel:DWORD dst_unused:UNUSED_PAD src0_sel:DWORD src1_sel:WORD_1
	v_mad_u32_u24 v58, v58, s17, v81
	s_mov_b32 s18, 16
	ds_write_b64 v58, v[56:57]
	s_cbranch_vccz .LBB0_1196
	v_mov_b32_e32 v132, v144
	v_mov_b32_e32 v133, v145
	v_mov_b32_e32 v134, v146
	v_mov_b32_e32 v135, v147
	v_mov_b32_e32 v136, v148
	v_mov_b32_e32 v137, v149
	v_mov_b32_e32 v138, v150
	v_mov_b32_e32 v139, v151
	v_mov_b32_e32 v140, v152
	v_mov_b32_e32 v141, v153
	v_mov_b32_e32 v142, v154
	v_mov_b32_e32 v143, v155
